# dense sparse-attention mask init: 2 VALU per element (bfe_i32+bfi) instead of and+cmp+cndmask
# speedup vs baseline: 1.0041x; 1.0041x over previous
; #define LAS __attribute__((address_space(3)))
; __device__ __forceinline__ void phaseB(const Params& p, LAS unsigned char* lds, int wv) {
;     ...
;                 { const unsigned w0 = mrow[2 * t] >> (8 * hi), w1 = mrow[2 * t + 1] >> (8 * hi);
;                   selm = (w0 & 0xffu) | ((w0 >> 8) & 0xff00u) | ((w1 & 0xffu) << 16) | ((w1 << 8) & 0xff000000u); }
;                 float sacc0 = 0.f, sacc1 = 0.f;
; #pragma unroll
;                 for (int hf = 0; hf < 2; ++hf) {
;                     f32x16 s0, s1;
; #pragma unroll
;                     for (int r = 0; r < 16; ++r) { const float cm = ((selm >> (16 * hf + r)) & 1u) ? 0.f : -1e30f; s0[r] = cm; s1[r] = cm; }
;                     const LAS unsigned char* kp = Kb + (32 * hf + pi32(r32)) * A_KROW + g * 128 + hi * 16;
; #pragma unroll
;                     for (int ds = 0; ds < 4; ++ds) { const bf16x8 kf = *(const LAS bf16x8*)(kp + 32 * ds);
;                         s0 = __builtin_amdgcn_mfma_f32_32x32x16_bf16(kf, qf2[0][ds], s0, 0, 0, 0); s1 = __builtin_amdgcn_mfma_f32_32x32x16_bf16(kf, qf2[1][ds], s1, 0, 0, 0); }
;                     if (!near) {
; #pragma unroll
;                         for (int r = 0; r < 16; ++r) { s0[r] = __builtin_amdgcn_exp2f(s0[r]); s1[r] = __builtin_amdgcn_exp2f(s1[r]); }
.LBB0_739:
	v_add_u32_e32 v64, -4, v242
	ds_read_b64 v[128:129], v64
	s_cmp_le_u32 s16, s13
	s_cselect_b64 s[4:5], -1, 0
	s_bitcmp1_b32 s15, 0
	s_cselect_b32 s6, 0x9400, 0
	s_add_i32 s17, s6, 0
	s_add_i32 s6, s17, s12
	v_add_u32_e32 v64, s6, v208
	s_mov_b64 s[6:7], -1
	s_waitcnt lgkmcnt(0)
	v_lshrrev_b32_e32 v68, v235, v128
	v_add_u32_e32 v128, v64, v239
	ds_read_b128 v[64:67], v128
	v_bfe_i32 v96, v68, 0, 1
	v_bfe_i32 v97, v68, 1, 1
	v_bfe_i32 v98, v68, 2, 1
	v_bfe_i32 v99, v68, 3, 1
	v_bfe_i32 v100, v68, 4, 1
	v_bfe_i32 v101, v68, 5, 1
	v_bfe_i32 v102, v68, 6, 1
	v_bfe_i32 v103, v68, 7, 1
	v_bfe_i32 v104, v68, 16, 1
	v_bfe_i32 v105, v68, 17, 1
	v_bfe_i32 v106, v68, 18, 1
	v_bfe_i32 v107, v68, 19, 1
	v_bfe_i32 v108, v68, 20, 1
	v_bfe_i32 v109, v68, 21, 1
	v_bfe_i32 v110, v68, 22, 1
	v_bfe_i32 v111, v68, 23, 1
	ds_read_b128 v[68:71], v128 offset:32
	v_bfi_b32 v96, v96, 0, v231
	v_bfi_b32 v97, v97, 0, v231
	v_bfi_b32 v98, v98, 0, v231
	v_bfi_b32 v99, v99, 0, v231
	v_bfi_b32 v100, v100, 0, v231
	v_bfi_b32 v101, v101, 0, v231
	v_bfi_b32 v102, v102, 0, v231
	v_bfi_b32 v103, v103, 0, v231
	v_bfi_b32 v104, v104, 0, v231
	v_bfi_b32 v105, v105, 0, v231
	v_bfi_b32 v106, v106, 0, v231
	v_bfi_b32 v107, v107, 0, v231
	v_bfi_b32 v108, v108, 0, v231
	v_bfi_b32 v109, v109, 0, v231
	v_bfi_b32 v110, v110, 0, v231
	v_bfi_b32 v111, v111, 0, v231
	s_and_b64 vcc, exec, s[4:5]
	s_waitcnt vmcnt(7) lgkmcnt(1)
	v_mfma_f32_32x32x16_bf16 v[112:127], v[64:67], v[176:179], v[96:111]
	s_waitcnt vmcnt(3)
	v_mfma_f32_32x32x16_bf16 v[96:111], v[64:67], v[192:195], v[96:111]
	s_waitcnt lgkmcnt(0)
	v_mfma_f32_32x32x16_bf16 v[112:127], v[68:71], v[180:183], v[112:127]
	s_waitcnt vmcnt(2)
	v_mfma_f32_32x32x16_bf16 v[96:111], v[68:71], v[196:199], v[96:111]
	ds_read_b128 v[64:67], v128 offset:64
	ds_read_b128 v[68:71], v128 offset:96
	s_waitcnt lgkmcnt(1)
	v_mfma_f32_32x32x16_bf16 v[112:127], v[64:67], v[184:187], v[112:127]
	s_waitcnt vmcnt(1)
	v_mfma_f32_32x32x16_bf16 v[96:111], v[64:67], v[200:203], v[96:111]
	s_waitcnt lgkmcnt(0)
	v_mfma_f32_32x32x16_bf16 v[112:127], v[68:71], v[188:191], v[112:127]
	s_waitcnt vmcnt(0)
	v_mfma_f32_32x32x16_bf16 v[96:111], v[68:71], v[204:207], v[96:111]
	s_cbranch_vccz .LBB0_741
	s_nop 8
	v_exp_f32_e32 v64, v112
	s_nop 0
	v_exp_f32_e32 v80, v96
	v_exp_f32_e32 v65, v113
	v_exp_f32_e32 v81, v97
	v_exp_f32_e32 v66, v114
	v_exp_f32_e32 v82, v98
	v_exp_f32_e32 v67, v115
	v_exp_f32_e32 v83, v99
	v_exp_f32_e32 v68, v116
	v_exp_f32_e32 v84, v100
	v_exp_f32_e32 v69, v117
	v_exp_f32_e32 v85, v101
	v_exp_f32_e32 v70, v118
	v_exp_f32_e32 v86, v102
	v_exp_f32_e32 v71, v119
	v_exp_f32_e32 v87, v103
	v_exp_f32_e32 v72, v120
	v_exp_f32_e32 v88, v104
	v_exp_f32_e32 v73, v121
	v_exp_f32_e32 v89, v105
	v_exp_f32_e32 v74, v122
	v_exp_f32_e32 v90, v106
	v_exp_f32_e32 v75, v123
	v_exp_f32_e32 v91, v107
	v_exp_f32_e32 v76, v124
	v_exp_f32_e32 v92, v108
	v_exp_f32_e32 v77, v125
	v_exp_f32_e32 v93, v109
	v_exp_f32_e32 v78, v126
	v_exp_f32_e32 v94, v110
	v_exp_f32_e32 v79, v127
	s_mov_b64 s[6:7], 0

; __device__ __forceinline__ void phaseB(const Params& p, LAS unsigned char* lds, int wv) {
;     ...
;                 for (int hf = 0; hf < 2; ++hf) {
;                     f32x16 s0, s1;
; #pragma unroll
;                     for (int r = 0; r < 16; ++r) { const float cm = ((selm >> (16 * hf + r)) & 1u) ? 0.f : -1e30f; s0[r] = cm; s1[r] = cm; }
;                     const LAS unsigned char* kp = Kb + (32 * hf + pi32(r32)) * A_KROW + g * 128 + hi * 16;
; #pragma unroll
;                     for (int ds = 0; ds < 4; ++ds) { const bf16x8 kf = *(const LAS bf16x8*)(kp + 32 * ds);
;                         s0 = __builtin_amdgcn_mfma_f32_32x32x16_bf16(kf, qf2[0][ds], s0, 0, 0, 0); s1 = __builtin_amdgcn_mfma_f32_32x32x16_bf16(kf, qf2[1][ds], s1, 0, 0, 0); }
;                     if (!near) {
; #pragma unroll
;                         for (int r = 0; r < 16; ++r) { s0[r] = __builtin_amdgcn_exp2f(s0[r]); s1[r] = __builtin_amdgcn_exp2f(s1[r]); }
;                     } else {
;                         int ib = 223 - (qpos - k0 - 8 * hi - 32 * hf); asm volatile("" : "+v"(ib));
;                         const LAS float* tp0 = Tb + (2 * hp) * 320 + ib; const LAS float* tp1 = tp0 + 320;
; #pragma unroll
;                         for (int r = 0; r < 16; ++r) { s0[r] = __builtin_amdgcn_exp2f(s0[r] + tp0[16 * (r >> 3) + (r & 7)]); s1[r] = __builtin_amdgcn_exp2f(s1[r] + tp1[16 * (r >> 3) + (r & 7)]); }
;                     }
; #pragma unroll
;                     for (int r = 0; r < 16; ++r) { sacc0 += s0[r]; sacc1 += s1[r]; }
; #pragma unroll
;                     for (int jj = 0; jj < 2; ++jj) {
;                         const int j = 2 * hf + jj, rb = 8 * jj;
;                         u32x4 pw0, pw1;
;                         pw0.x = cvt_pk_bf16(s0[rb], s0[rb + 1]); pw0.y = cvt_pk_bf16(s0[rb + 2], s0[rb + 3]); pw0.z = cvt_pk_bf16(s0[rb + 4], s0[rb + 5]); pw0.w = cvt_pk_bf16(s0[rb + 6], s0[rb + 7]);
;                         pw1.x = cvt_pk_bf16(s1[rb], s1[rb + 1]); pw1.y = cvt_pk_bf16(s1[rb + 2], s1[rb + 3]); pw1.z = cvt_pk_bf16(s1[rb + 4], s1[rb + 5]); pw1.w = cvt_pk_bf16(s1[rb + 6], s1[rb + 7]);
;                         const bf16x8 pa0 = __builtin_bit_cast(bf16x8, pw0), pa1 = __builtin_bit_cast(bf16x8, pw1);
;                         const LAS unsigned char* vp = Vb + (16 * j + 8 * hi + ((lane & 15) >> 2)) * A_VROW + (g * 64 + 16 * ((lane >> 4) & 1) + 4 * (lane & 3)) * 2;
.LBB0_743:
	v_add_u32_e32 v95, s17, v241
	v_add_u32_e32 v245, v95, v240
	v_cvt_pk_bf16_f32 v96, v64, v65
	v_cvt_pk_bf16_f32 v97, v66, v67
	v_cvt_pk_bf16_f32 v98, v68, v69
	v_cvt_pk_bf16_f32 v99, v70, v71
	v_cvt_pk_bf16_f32 v100, v80, v81
	v_cvt_pk_bf16_f32 v101, v82, v83
	v_cvt_pk_bf16_f32 v102, v84, v85
	v_cvt_pk_bf16_f32 v103, v86, v87
	s_nop 6
	ds_read_b64_tr_b16 v[104:105], v245 offset:17408
	ds_read_b64_tr_b16 v[106:107], v245 offset:18688
	ds_read_b64_tr_b16 v[114:115], v245 offset:18752
	ds_read_b64_tr_b16 v[112:113], v245 offset:17472
	s_waitcnt lgkmcnt(2)
	v_mfma_f32_32x32x16_bf16 v[48:63], v[96:99], v[104:107], v[48:63]
	v_exp_f32_e32 v244, v111
	v_lshrrev_b32_e32 v95, v235, v129
	v_mfma_f32_32x32x16_bf16 v[16:31], v[100:103], v[104:107], v[16:31]
	s_waitcnt lgkmcnt(0)
	v_mfma_f32_32x32x16_bf16 v[32:47], v[96:99], v[112:115], v[32:47]
	v_cvt_pk_bf16_f32 v96, v72, v73
	v_cvt_pk_bf16_f32 v97, v74, v75
	v_cvt_pk_bf16_f32 v98, v76, v77
	v_cvt_pk_bf16_f32 v99, v78, v79
	v_mfma_f32_32x32x16_bf16 v[0:15], v[100:103], v[112:115], v[0:15]
	v_cvt_pk_bf16_f32 v100, v88, v89
	v_cvt_pk_bf16_f32 v101, v90, v91
	v_cvt_pk_bf16_f32 v102, v92, v93
	v_cvt_pk_bf16_f32 v103, v94, v244
	ds_read_b64_tr_b16 v[104:105], v245 offset:22528
	ds_read_b64_tr_b16 v[106:107], v245 offset:23808
	ds_read_b64_tr_b16 v[110:111], v245 offset:23872
	ds_read_b64_tr_b16 v[108:109], v245 offset:22592
	s_waitcnt lgkmcnt(2)
	v_mfma_f32_32x32x16_bf16 v[48:63], v[96:99], v[104:107], v[48:63]
	v_mfma_f32_32x32x16_bf16 v[16:31], v[100:103], v[104:107], v[16:31]
	s_waitcnt lgkmcnt(0)
	v_mfma_f32_32x32x16_bf16 v[32:47], v[96:99], v[108:111], v[32:47]
	v_mfma_f32_32x32x16_bf16 v[0:15], v[100:103], v[108:111], v[0:15]
	v_bfe_i32 v96, v95, 0, 1
	v_bfe_i32 v97, v95, 1, 1
	v_bfe_i32 v98, v95, 2, 1
	v_bfe_i32 v99, v95, 3, 1
	v_bfe_i32 v100, v95, 4, 1
	v_bfe_i32 v101, v95, 5, 1
	v_bfe_i32 v102, v95, 6, 1
	v_bfe_i32 v103, v95, 7, 1
	v_bfe_i32 v104, v95, 16, 1
	v_bfe_i32 v105, v95, 17, 1
	v_bfe_i32 v106, v95, 18, 1
	v_bfe_i32 v107, v95, 19, 1
	v_bfe_i32 v108, v95, 20, 1
	v_bfe_i32 v109, v95, 21, 1
	v_bfe_i32 v110, v95, 22, 1
	v_bfe_i32 v111, v95, 23, 1
	ds_read_b128 v[112:115], v128 offset:8704
	ds_read_b128 v[116:119], v128 offset:8736
	v_bfi_b32 v96, v96, 0, v231
	v_bfi_b32 v97, v97, 0, v231
	v_bfi_b32 v98, v98, 0, v231
	v_bfi_b32 v99, v99, 0, v231
	v_bfi_b32 v100, v100, 0, v231
	v_bfi_b32 v101, v101, 0, v231
	v_bfi_b32 v102, v102, 0, v231
	v_bfi_b32 v103, v103, 0, v231
	v_bfi_b32 v104, v104, 0, v231
	v_bfi_b32 v105, v105, 0, v231
	v_bfi_b32 v106, v106, 0, v231
	v_bfi_b32 v107, v107, 0, v231
	v_bfi_b32 v108, v108, 0, v231
	v_bfi_b32 v109, v109, 0, v231
	v_bfi_b32 v110, v110, 0, v231
	v_bfi_b32 v111, v111, 0, v231
	s_andn2_b64 vcc, exec, s[4:5]
	s_mov_b64 s[4:5], -1
	s_waitcnt lgkmcnt(1)
	v_mfma_f32_32x32x16_bf16 v[144:159], v[112:115], v[176:179], v[96:111]
	v_mfma_f32_32x32x16_bf16 v[96:111], v[112:115], v[192:195], v[96:111]
	s_waitcnt lgkmcnt(0)
	v_mfma_f32_32x32x16_bf16 v[144:159], v[116:119], v[180:183], v[144:159]
	v_mfma_f32_32x32x16_bf16 v[96:111], v[116:119], v[196:199], v[96:111]
	ds_read_b128 v[112:115], v128 offset:8768
	ds_read_b128 v[116:119], v128 offset:8800
	s_waitcnt lgkmcnt(1)
	v_mfma_f32_32x32x16_bf16 v[144:159], v[112:115], v[184:187], v[144:159]
	v_mfma_f32_32x32x16_bf16 v[96:111], v[112:115], v[200:203], v[96:111]
	s_waitcnt lgkmcnt(0)
	v_mfma_f32_32x32x16_bf16 v[144:159], v[116:119], v[188:191], v[144:159]
	v_mfma_f32_32x32x16_bf16 v[96:111], v[116:119], v[204:207], v[96:111]
	s_cbranch_vccnz .LBB0_745
	s_nop 9
	v_exp_f32_e32 v112, v144
	v_exp_f32_e32 v128, v96
	v_exp_f32_e32 v113, v145
	v_exp_f32_e32 v129, v97
	v_exp_f32_e32 v114, v146
	v_exp_f32_e32 v130, v98
	v_exp_f32_e32 v115, v147
	v_exp_f32_e32 v131, v99
	v_exp_f32_e32 v116, v148
	v_exp_f32_e32 v132, v100
	v_exp_f32_e32 v117, v149
	v_exp_f32_e32 v133, v101
	v_exp_f32_e32 v118, v150
	v_exp_f32_e32 v134, v102
	v_exp_f32_e32 v119, v151
	v_exp_f32_e32 v135, v103
	v_exp_f32_e32 v120, v152
	v_exp_f32_e32 v136, v104
	v_exp_f32_e32 v121, v153
	v_exp_f32_e32 v137, v105
	v_exp_f32_e32 v122, v154
	v_exp_f32_e32 v138, v106
	v_exp_f32_e32 v123, v155
	v_exp_f32_e32 v139, v107
	v_exp_f32_e32 v124, v156
	v_exp_f32_e32 v140, v108
	v_exp_f32_e32 v125, v157
	v_exp_f32_e32 v141, v109
	v_exp_f32_e32 v126, v158
	v_exp_f32_e32 v142, v110
	v_exp_f32_e32 v127, v159
	s_mov_b64 s[4:5], 0
